# hand-written P8 gated-FFN epilogue: conv taps as v_fmac_f32_dpp on pre-selected cur/prv, packed f32 sigmoid/gate, 4-wide batches; on top of trim15
# speedup vs baseline: 1.0060x; 1.0060x over previous
;     __device__ __forceinline__ void operator()(const f32x4 (&acc)[2][2][4][2], const Unit& u, int wr, int wc, int fr, int fq) const {
;         const int ch0 = u.pn * 128 + wc * 32 + 8 * fq;
;         f32x4 w0[2], w1[2], w2[2];
; #pragma unroll
;         for (int n = 0; n < 2; ++n) { w0[n] = *(const f32x4*)(cw + ch0 + 4 * n); w1[n] = *(const f32x4*)(cw + ldh + ch0 + 4 * n); w2[n] = *(const f32x4*)(cw + 2 * ldh + ch0 + 4 * n); }
;         const bool f1 = fr >= 1, f2 = fr >= 2;
; #pragma unroll
;         for (int ai = 0; ai < 2; ++ai) {
;             const int blk = u.pm * 4 + ai * 2 + wr;
; #pragma unroll
;             for (int m = 0; m < 4; ++m) {
;                 const size_t row = (size_t)(u.pm * BM + ai * HALF + wr * 64 + m * 16 + fr);
;                 float hg[8];
; #pragma unroll
;                 for (int n = 0; n < 2; ++n)
; #pragma unroll
;                     for (int i = 0; i < 4; ++i) {
;                         const float cur = acc[ai][0][m][n][i], prv = (m > 0) ? acc[ai][0][m > 0 ? m - 1 : 0][n][i] : cur;
;                         const float r1c = dpp_ror1(cur), r1p = dpp_ror1(prv), r2c = dpp_ror2(cur), r2p = dpp_ror2(prv);
;                         const float tm1 = f1 ? r1c : r1p, tm2 = f2 ? r2c : r2p;
;                         const float cv = w0[n][i] * tm2 + w1[n][i] * tm1 + w2[n][i] * cur;
;                         hg[4 * n + i] = cv * sigmoidf_(cv) * acc[ai][1][m][n][i];
;                     }
;                 if (m == 0 && fr < 2) {
;                     const f32x4 a0 = acc[ai][0][0][0], a1 = acc[ai][0][0][1], v0 = acc[ai][1][0][0], v1 = acc[ai][1][0][1];
;                     u32x4 wa, wv; wa.x = cvt_pk_bf16(a0[0], a0[1]); wa.y = cvt_pk_bf16(a0[2], a0[3]); wa.z = cvt_pk_bf16(a1[0], a1[1]); wa.w = cvt_pk_bf16(a1[2], a1[3]);
;                     wv.x = cvt_pk_bf16(v0[0], v0[1]); wv.y = cvt_pk_bf16(v0[2], v0[3]); wv.z = cvt_pk_bf16(v1[0], v1[1]); wv.w = cvt_pk_bf16(v1[2], v1[3]);
;                     *(u32x4*)(side + ((size_t)blk * 6 + 2 + fr) * ldh + ch0) = wa; *(u32x4*)(side + ((size_t)blk * 6 + 4 + fr) * ldh + ch0) = wv;
;                 } else {
;                     u32x4 w; w.x = cvt_pk_bf16(hg[0], hg[1]); w.y = cvt_pk_bf16(hg[2], hg[3]); w.z = cvt_pk_bf16(hg[4], hg[5]); w.w = cvt_pk_bf16(hg[6], hg[7]);
;                     *(u32x4*)(HG + row * ldh + ch0) = w;
;                 }
.LBB0_713:
	v_lshl_or_b32 v70, s15, 7, v221
	v_lshlrev_b32_e32 v71, 2, v70
	global_load_dwordx4 v[224:227], v71, s[52:53]
	global_load_dwordx4 v[228:231], v71, s[52:53] offset:16
	global_load_dwordx4 v[232:235], v71, s[56:57]
	global_load_dwordx4 v[236:239], v71, s[56:57] offset:16
	global_load_dwordx4 v[192:195], v71, s[58:59]
	global_load_dwordx4 v[196:199], v71, s[58:59] offset:16
	s_mov_b32 s65, 0x100000
	v_and_b32_e32 v72, 15, v161
	v_cmp_eq_u32_e64 s[16:17], 15, v72
	v_lshlrev_b32_e32 v188, 1, v70
	v_mov_b32_e32 v189, 0
	v_lshl_add_u32 v73, s14, 8, v161
	v_mad_u64_u32 v[170:171], vcc, v73, s92, v[188:189]
	s_lshl_b32 s14, s14, 2
	s_add_i32 s14, s14, s8
	s_mul_i32 s14, s14, 6
	v_add_u32_e32 v73, s14, v72
	v_lshl_add_u64 v[170:171], s[50:51], 0, v[170:171]
	v_mad_u64_u32 v[190:191], vcc, v73, s92, v[188:189]
	s_mov_b64 s[22:23], exec
	s_mov_b32 s14, 0xbfb8aa3b
	s_mov_b32 s15, 0xbfb8aa3b
	s_mov_b32 s24, 1.0
	s_mov_b32 s25, 1.0
	v_lshl_add_u64 v[190:191], s[48:49], 0, v[190:191]
	s_waitcnt vmcnt(0)
	v_cvt_pk_bf16_f32 v154, v142, v143
	v_cvt_pk_bf16_f32 v155, v144, v145
	v_cvt_pk_bf16_f32 v156, v130, v131
	v_cvt_pk_bf16_f32 v157, v132, v133
	v_cvt_pk_bf16_f32 v204, v150, v151
	v_cvt_pk_bf16_f32 v205, v152, v153
	v_cvt_pk_bf16_f32 v206, v146, v147
	v_cvt_pk_bf16_f32 v207, v148, v149
	v_add_co_u32_e32 v188, vcc, 0xac00, v190
	v_addc_co_u32_e32 v189, vcc, 0, v191, vcc
	v_add_co_u32_e32 v208, vcc, 0x15800, v190
	v_addc_co_u32_e32 v209, vcc, 0, v191, vcc
	s_andn2_b64 exec, s[22:23], s[40:41]
	global_store_dwordx4 v[188:189], v[154:157], off
	global_store_dwordx4 v[208:209], v[204:207], off
	s_mov_b64 exec, s[22:23]
	s_nop 4
	v_pk_mul_f32 v[70:71], v[192:193], v[142:143]
	v_pk_mul_f32 v[72:73], v[194:195], v[144:145]
	v_fmac_f32_dpp v70, v142, v232 row_ror:1 row_mask:0xf bank_mask:0xf
	v_fmac_f32_dpp v71, v143, v233 row_ror:1 row_mask:0xf bank_mask:0xf
	v_fmac_f32_dpp v72, v144, v234 row_ror:1 row_mask:0xf bank_mask:0xf
	v_fmac_f32_dpp v73, v145, v235 row_ror:1 row_mask:0xf bank_mask:0xf
	v_fmac_f32_dpp v70, v142, v224 row_ror:2 row_mask:0xf bank_mask:0xf
	v_fmac_f32_dpp v71, v143, v225 row_ror:2 row_mask:0xf bank_mask:0xf
	v_fmac_f32_dpp v72, v144, v226 row_ror:2 row_mask:0xf bank_mask:0xf
	v_fmac_f32_dpp v73, v145, v227 row_ror:2 row_mask:0xf bank_mask:0xf
	v_pk_mul_f32 v[200:201], v[70:71], s[14:15]
	v_pk_mul_f32 v[202:203], v[72:73], s[14:15]
	v_exp_f32_e32 v200, v200
	v_exp_f32_e32 v201, v201
	v_exp_f32_e32 v202, v202
	v_exp_f32_e32 v203, v203
	v_pk_add_f32 v[200:201], v[200:201], s[24:25]
	v_pk_add_f32 v[202:203], v[202:203], s[24:25]
	v_rcp_f32_e32 v200, v200
	v_rcp_f32_e32 v201, v201
	v_rcp_f32_e32 v202, v202
	v_rcp_f32_e32 v203, v203
	v_pk_mul_f32 v[70:71], v[70:71], v[200:201]
	v_pk_mul_f32 v[72:73], v[72:73], v[202:203]
	v_pk_mul_f32 v[150:151], v[150:151], v[70:71]
	v_pk_mul_f32 v[152:153], v[152:153], v[72:73]
	v_pk_mul_f32 v[70:71], v[196:197], v[130:131]
	v_pk_mul_f32 v[72:73], v[198:199], v[132:133]
	v_fmac_f32_dpp v70, v130, v236 row_ror:1 row_mask:0xf bank_mask:0xf
	v_fmac_f32_dpp v71, v131, v237 row_ror:1 row_mask:0xf bank_mask:0xf
	v_fmac_f32_dpp v72, v132, v238 row_ror:1 row_mask:0xf bank_mask:0xf
	v_fmac_f32_dpp v73, v133, v239 row_ror:1 row_mask:0xf bank_mask:0xf
	v_fmac_f32_dpp v70, v130, v228 row_ror:2 row_mask:0xf bank_mask:0xf
	v_fmac_f32_dpp v71, v131, v229 row_ror:2 row_mask:0xf bank_mask:0xf
	v_fmac_f32_dpp v72, v132, v230 row_ror:2 row_mask:0xf bank_mask:0xf
	v_fmac_f32_dpp v73, v133, v231 row_ror:2 row_mask:0xf bank_mask:0xf
	v_pk_mul_f32 v[200:201], v[70:71], s[14:15]
	v_pk_mul_f32 v[202:203], v[72:73], s[14:15]
	v_exp_f32_e32 v200, v200
	v_exp_f32_e32 v201, v201
	v_exp_f32_e32 v202, v202
	v_exp_f32_e32 v203, v203
	v_pk_add_f32 v[200:201], v[200:201], s[24:25]
	v_pk_add_f32 v[202:203], v[202:203], s[24:25]
	v_rcp_f32_e32 v200, v200
	v_rcp_f32_e32 v201, v201
	v_rcp_f32_e32 v202, v202
	v_rcp_f32_e32 v203, v203
	v_pk_mul_f32 v[70:71], v[70:71], v[200:201]
	v_pk_mul_f32 v[72:73], v[72:73], v[202:203]
	v_pk_mul_f32 v[146:147], v[146:147], v[70:71]
	v_pk_mul_f32 v[148:149], v[148:149], v[72:73]
	v_cvt_pk_bf16_f32 v150, v150, v151
	v_cvt_pk_bf16_f32 v151, v152, v153
	v_cvt_pk_bf16_f32 v152, v146, v147
	v_cvt_pk_bf16_f32 v153, v148, v149
	s_and_b64 exec, s[22:23], s[40:41]
	global_store_dwordx4 v[170:171], v[150:153], off
	s_mov_b64 exec, s[22:23]
	v_cndmask_b32_e64 v200, v138, v142, s[16:17]
	v_cndmask_b32_e64 v201, v139, v143, s[16:17]
	v_cndmask_b32_e64 v202, v140, v144, s[16:17]
	v_cndmask_b32_e64 v203, v141, v145, s[16:17]
	v_cndmask_b32_e64 v204, v138, v142, s[42:43]
	v_cndmask_b32_e64 v205, v139, v143, s[42:43]
	v_cndmask_b32_e64 v206, v140, v144, s[42:43]
	v_cndmask_b32_e64 v207, v141, v145, s[42:43]
	v_pk_mul_f32 v[70:71], v[192:193], v[138:139]
	v_pk_mul_f32 v[72:73], v[194:195], v[140:141]
	v_fmac_f32_dpp v70, v200, v232 row_ror:1 row_mask:0xf bank_mask:0xf
	v_fmac_f32_dpp v71, v201, v233 row_ror:1 row_mask:0xf bank_mask:0xf
	v_fmac_f32_dpp v72, v202, v234 row_ror:1 row_mask:0xf bank_mask:0xf
	v_fmac_f32_dpp v73, v203, v235 row_ror:1 row_mask:0xf bank_mask:0xf
	v_fmac_f32_dpp v70, v204, v224 row_ror:2 row_mask:0xf bank_mask:0xf
	v_fmac_f32_dpp v71, v205, v225 row_ror:2 row_mask:0xf bank_mask:0xf
	v_fmac_f32_dpp v72, v206, v226 row_ror:2 row_mask:0xf bank_mask:0xf
	v_fmac_f32_dpp v73, v207, v227 row_ror:2 row_mask:0xf bank_mask:0xf
	v_pk_mul_f32 v[200:201], v[70:71], s[14:15]
	v_pk_mul_f32 v[202:203], v[72:73], s[14:15]
	v_exp_f32_e32 v200, v200
	v_exp_f32_e32 v201, v201
	v_exp_f32_e32 v202, v202
	v_exp_f32_e32 v203, v203
	v_pk_add_f32 v[200:201], v[200:201], s[24:25]
	v_pk_add_f32 v[202:203], v[202:203], s[24:25]
; __device__ __forceinline__ unsigned cvt_pk_bf16(float lo, float hi) { unsigned r; asm volatile("v_cvt_pk_bf16_f32 %0, %1, %2" : "=v"(r) : "v"(lo), "v"(hi)); return r; }
; __device__ __forceinline__ float sigmoidf_(float x) { return __builtin_amdgcn_rcpf(1.0f + __expf(-x)); }
; __device__ __forceinline__ float dpp_ror1(float x) { return __int_as_float(__builtin_amdgcn_update_dpp(0, __float_as_int(x), 0x121, 0xF, 0xF, true)); }
;     __device__ __forceinline__ void operator()(const f32x4 (&acc)[2][2][4][2], const Unit& u, int wr, int wc, int fr, int fq) const {
;     ...
;             for (int m = 0; m < 4; ++m) {
;                 const size_t row = (size_t)(u.pm * BM + ai * HALF + wr * 64 + m * 16 + fr);
;                 float hg[8];
; #pragma unroll
;                 for (int n = 0; n < 2; ++n)
; #pragma unroll
;                     for (int i = 0; i < 4; ++i) {
;                         const float cur = acc[ai][0][m][n][i], prv = (m > 0) ? acc[ai][0][m > 0 ? m - 1 : 0][n][i] : cur;
;                         const float r1c = dpp_ror1(cur), r1p = dpp_ror1(prv), r2c = dpp_ror2(cur), r2p = dpp_ror2(prv);
;                         const float tm1 = f1 ? r1c : r1p, tm2 = f2 ? r2c : r2p;
;                         const float cv = w0[n][i] * tm2 + w1[n][i] * tm1 + w2[n][i] * cur;
;                         hg[4 * n + i] = cv * sigmoidf_(cv) * acc[ai][1][m][n][i];
;                     }
;                 if (m == 0 && fr < 2) {
;                     const f32x4 a0 = acc[ai][0][0][0], a1 = acc[ai][0][0][1], v0 = acc[ai][1][0][0], v1 = acc[ai][1][0][1];
;                     u32x4 wa, wv; wa.x = cvt_pk_bf16(a0[0], a0[1]); wa.y = cvt_pk_bf16(a0[2], a0[3]); wa.z = cvt_pk_bf16(a1[0], a1[1]); wa.w = cvt_pk_bf16(a1[2], a1[3]);
;                     wv.x = cvt_pk_bf16(v0[0], v0[1]); wv.y = cvt_pk_bf16(v0[2], v0[3]); wv.z = cvt_pk_bf16(v1[0], v1[1]); wv.w = cvt_pk_bf16(v1[2], v1[3]);
;                     *(u32x4*)(side + ((size_t)blk * 6 + 2 + fr) * ldh + ch0) = wa; *(u32x4*)(side + ((size_t)blk * 6 + 4 + fr) * ldh + ch0) = wv;
;                 } else {
;                     u32x4 w; w.x = cvt_pk_bf16(hg[0], hg[1]); w.y = cvt_pk_bf16(hg[2], hg[3]); w.z = cvt_pk_bf16(hg[4], hg[5]); w.w = cvt_pk_bf16(hg[6], hg[7]);
;                     *(u32x4*)(HG + row * ldh + ch0) = w;
;                 }
	v_rcp_f32_e32 v200, v200
	v_rcp_f32_e32 v201, v201
	v_rcp_f32_e32 v202, v202
	v_rcp_f32_e32 v203, v203
	v_pk_mul_f32 v[70:71], v[70:71], v[200:201]
	v_pk_mul_f32 v[72:73], v[72:73], v[202:203]
	v_pk_mul_f32 v[134:135], v[134:135], v[70:71]
	v_pk_mul_f32 v[136:137], v[136:137], v[72:73]
	v_cndmask_b32_e64 v200, v126, v130, s[16:17]
	v_cndmask_b32_e64 v201, v127, v131, s[16:17]
	v_cndmask_b32_e64 v202, v128, v132, s[16:17]
	v_cndmask_b32_e64 v203, v129, v133, s[16:17]
	v_cndmask_b32_e64 v204, v126, v130, s[42:43]
	v_cndmask_b32_e64 v205, v127, v131, s[42:43]
	v_cndmask_b32_e64 v206, v128, v132, s[42:43]
	v_cndmask_b32_e64 v207, v129, v133, s[42:43]
	v_pk_mul_f32 v[70:71], v[196:197], v[126:127]
	v_pk_mul_f32 v[72:73], v[198:199], v[128:129]
	v_fmac_f32_dpp v70, v200, v236 row_ror:1 row_mask:0xf bank_mask:0xf
	v_fmac_f32_dpp v71, v201, v237 row_ror:1 row_mask:0xf bank_mask:0xf
	v_fmac_f32_dpp v72, v202, v238 row_ror:1 row_mask:0xf bank_mask:0xf
	v_fmac_f32_dpp v73, v203, v239 row_ror:1 row_mask:0xf bank_mask:0xf
	v_fmac_f32_dpp v70, v204, v228 row_ror:2 row_mask:0xf bank_mask:0xf
	v_fmac_f32_dpp v71, v205, v229 row_ror:2 row_mask:0xf bank_mask:0xf
	v_fmac_f32_dpp v72, v206, v230 row_ror:2 row_mask:0xf bank_mask:0xf
	v_fmac_f32_dpp v73, v207, v231 row_ror:2 row_mask:0xf bank_mask:0xf
	v_pk_mul_f32 v[200:201], v[70:71], s[14:15]
	v_pk_mul_f32 v[202:203], v[72:73], s[14:15]
	v_exp_f32_e32 v200, v200
	v_exp_f32_e32 v201, v201
	v_exp_f32_e32 v202, v202
	v_exp_f32_e32 v203, v203
	v_pk_add_f32 v[200:201], v[200:201], s[24:25]
	v_pk_add_f32 v[202:203], v[202:203], s[24:25]
	v_rcp_f32_e32 v200, v200
	v_rcp_f32_e32 v201, v201
	v_rcp_f32_e32 v202, v202
	v_rcp_f32_e32 v203, v203
	v_pk_mul_f32 v[70:71], v[70:71], v[200:201]
	v_pk_mul_f32 v[72:73], v[72:73], v[202:203]
	v_pk_mul_f32 v[122:123], v[122:123], v[70:71]
	v_pk_mul_f32 v[124:125], v[124:125], v[72:73]
	v_cvt_pk_bf16_f32 v134, v134, v135
	v_cvt_pk_bf16_f32 v135, v136, v137
	v_cvt_pk_bf16_f32 v136, v122, v123
	v_cvt_pk_bf16_f32 v137, v124, v125
	v_add_co_u32_e32 v170, vcc, 0x56000, v170
	v_addc_co_u32_e32 v171, vcc, 0, v171, vcc
	global_store_dwordx4 v[170:171], v[134:137], off
	v_cndmask_b32_e64 v200, v118, v138, s[16:17]
	v_cndmask_b32_e64 v201, v119, v139, s[16:17]
	v_cndmask_b32_e64 v202, v120, v140, s[16:17]
	v_cndmask_b32_e64 v203, v121, v141, s[16:17]
	v_cndmask_b32_e64 v204, v118, v138, s[42:43]
	v_cndmask_b32_e64 v205, v119, v139, s[42:43]
	v_cndmask_b32_e64 v206, v120, v140, s[42:43]
	v_cndmask_b32_e64 v207, v121, v141, s[42:43]
	v_pk_mul_f32 v[70:71], v[192:193], v[118:119]
	v_pk_mul_f32 v[72:73], v[194:195], v[120:121]
	v_fmac_f32_dpp v70, v200, v232 row_ror:1 row_mask:0xf bank_mask:0xf
	v_fmac_f32_dpp v71, v201, v233 row_ror:1 row_mask:0xf bank_mask:0xf
	v_fmac_f32_dpp v72, v202, v234 row_ror:1 row_mask:0xf bank_mask:0xf
	v_fmac_f32_dpp v73, v203, v235 row_ror:1 row_mask:0xf bank_mask:0xf
	v_fmac_f32_dpp v70, v204, v224 row_ror:2 row_mask:0xf bank_mask:0xf
	v_fmac_f32_dpp v71, v205, v225 row_ror:2 row_mask:0xf bank_mask:0xf
	v_fmac_f32_dpp v72, v206, v226 row_ror:2 row_mask:0xf bank_mask:0xf
	v_fmac_f32_dpp v73, v207, v227 row_ror:2 row_mask:0xf bank_mask:0xf
	v_pk_mul_f32 v[200:201], v[70:71], s[14:15]
	v_pk_mul_f32 v[202:203], v[72:73], s[14:15]
	v_exp_f32_e32 v200, v200
	v_exp_f32_e32 v201, v201
	v_exp_f32_e32 v202, v202
	v_exp_f32_e32 v203, v203
	v_pk_add_f32 v[200:201], v[200:201], s[24:25]
	v_pk_add_f32 v[202:203], v[202:203], s[24:25]
	v_rcp_f32_e32 v200, v200
	v_rcp_f32_e32 v201, v201
	v_rcp_f32_e32 v202, v202
	v_rcp_f32_e32 v203, v203
	v_pk_mul_f32 v[70:71], v[70:71], v[200:201]
	v_pk_mul_f32 v[72:73], v[72:73], v[202:203]
	v_pk_mul_f32 v[114:115], v[114:115], v[70:71]
	v_pk_mul_f32 v[116:117], v[116:117], v[72:73]
	v_cndmask_b32_e64 v200, v110, v126, s[16:17]
	v_cndmask_b32_e64 v201, v111, v127, s[16:17]
	v_cndmask_b32_e64 v202, v112, v128, s[16:17]
	v_cndmask_b32_e64 v203, v113, v129, s[16:17]
	v_cndmask_b32_e64 v204, v110, v126, s[42:43]
	v_cndmask_b32_e64 v205, v111, v127, s[42:43]
	v_cndmask_b32_e64 v206, v112, v128, s[42:43]
	v_cndmask_b32_e64 v207, v113, v129, s[42:43]
	v_pk_mul_f32 v[70:71], v[196:197], v[110:111]
	v_pk_mul_f32 v[72:73], v[198:199], v[112:113]
	v_fmac_f32_dpp v70, v200, v236 row_ror:1 row_mask:0xf bank_mask:0xf
	v_fmac_f32_dpp v71, v201, v237 row_ror:1 row_mask:0xf bank_mask:0xf
	v_fmac_f32_dpp v72, v202, v238 row_ror:1 row_mask:0xf bank_mask:0xf
	v_fmac_f32_dpp v73, v203, v239 row_ror:1 row_mask:0xf bank_mask:0xf
	v_fmac_f32_dpp v70, v204, v228 row_ror:2 row_mask:0xf bank_mask:0xf
	v_fmac_f32_dpp v71, v205, v229 row_ror:2 row_mask:0xf bank_mask:0xf
	v_fmac_f32_dpp v72, v206, v230 row_ror:2 row_mask:0xf bank_mask:0xf
	v_fmac_f32_dpp v73, v207, v231 row_ror:2 row_mask:0xf bank_mask:0xf
	v_pk_mul_f32 v[200:201], v[70:71], s[14:15]
	v_pk_mul_f32 v[202:203], v[72:73], s[14:15]
	v_exp_f32_e32 v200, v200
	v_exp_f32_e32 v201, v201
	v_exp_f32_e32 v202, v202
	v_exp_f32_e32 v203, v203
	v_pk_add_f32 v[200:201], v[200:201], s[24:25]
	v_pk_add_f32 v[202:203], v[202:203], s[24:25]
	v_rcp_f32_e32 v200, v200
	v_rcp_f32_e32 v201, v201
	v_rcp_f32_e32 v202, v202
	v_rcp_f32_e32 v203, v203
	v_pk_mul_f32 v[70:71], v[70:71], v[200:201]
	v_pk_mul_f32 v[72:73], v[72:73], v[202:203]
	v_pk_mul_f32 v[106:107], v[106:107], v[70:71]
	v_pk_mul_f32 v[108:109], v[108:109], v[72:73]
	v_cvt_pk_bf16_f32 v114, v114, v115
	v_cvt_pk_bf16_f32 v115, v116, v117
	v_cvt_pk_bf16_f32 v116, v106, v107
	v_cvt_pk_bf16_f32 v117, v108, v109
	v_add_co_u32_e32 v170, vcc, 0x56000, v170
	v_addc_co_u32_e32 v171, vcc, 0, v171, vcc
	global_store_dwordx4 v[170:171], v[114:117], off
; __device__ __forceinline__ float sigmoidf_(float x) { return __builtin_amdgcn_rcpf(1.0f + __expf(-x)); }
;     __device__ __forceinline__ void operator()(const f32x4 (&acc)[2][2][4][2], const Unit& u, int wr, int wc, int fr, int fq) const {
;     ...
;             for (int m = 0; m < 4; ++m) {
;                 const size_t row = (size_t)(u.pm * BM + ai * HALF + wr * 64 + m * 16 + fr);
;                 float hg[8];
; #pragma unroll
;                 for (int n = 0; n < 2; ++n)
; #pragma unroll
;                     for (int i = 0; i < 4; ++i) {
;                         const float cur = acc[ai][0][m][n][i], prv = (m > 0) ? acc[ai][0][m > 0 ? m - 1 : 0][n][i] : cur;
;                         const float r1c = dpp_ror1(cur), r1p = dpp_ror1(prv), r2c = dpp_ror2(cur), r2p = dpp_ror2(prv);
;                         const float tm1 = f1 ? r1c : r1p, tm2 = f2 ? r2c : r2p;
;                         const float cv = w0[n][i] * tm2 + w1[n][i] * tm1 + w2[n][i] * cur;
;                         hg[4 * n + i] = cv * sigmoidf_(cv) * acc[ai][1][m][n][i];
;                     }
;                 if (m == 0 && fr < 2) {
;                     const f32x4 a0 = acc[ai][0][0][0], a1 = acc[ai][0][0][1], v0 = acc[ai][1][0][0], v1 = acc[ai][1][0][1];
;                     u32x4 wa, wv; wa.x = cvt_pk_bf16(a0[0], a0[1]); wa.y = cvt_pk_bf16(a0[2], a0[3]); wa.z = cvt_pk_bf16(a1[0], a1[1]); wa.w = cvt_pk_bf16(a1[2], a1[3]);
;                     wv.x = cvt_pk_bf16(v0[0], v0[1]); wv.y = cvt_pk_bf16(v0[2], v0[3]); wv.z = cvt_pk_bf16(v1[0], v1[1]); wv.w = cvt_pk_bf16(v1[2], v1[3]);
;                     *(u32x4*)(side + ((size_t)blk * 6 + 2 + fr) * ldh + ch0) = wa; *(u32x4*)(side + ((size_t)blk * 6 + 4 + fr) * ldh + ch0) = wv;
;                 } else {
;                     u32x4 w; w.x = cvt_pk_bf16(hg[0], hg[1]); w.y = cvt_pk_bf16(hg[2], hg[3]); w.z = cvt_pk_bf16(hg[4], hg[5]); w.w = cvt_pk_bf16(hg[6], hg[7]);
;                     *(u32x4*)(HG + row * ldh + ch0) = w;
;                 }
;                 if (m == 3 && fr >= 14) {
;                     const f32x4 a0 = acc[ai][0][3][0], a1 = acc[ai][0][3][1];
;                     u32x4 wa; wa.x = cvt_pk_bf16(a0[0], a0[1]); wa.y = cvt_pk_bf16(a0[2], a0[3]); wa.z = cvt_pk_bf16(a1[0], a1[1]); wa.w = cvt_pk_bf16(a1[2], a1[3]);
;                     *(u32x4*)(side + ((size_t)blk * 6 + (fr - 14)) * ldh + ch0) = wa;
;                 }
	v_cndmask_b32_e64 v200, v98, v118, s[16:17]
	v_cndmask_b32_e64 v201, v99, v119, s[16:17]
	v_cndmask_b32_e64 v202, v100, v120, s[16:17]
	v_cndmask_b32_e64 v203, v101, v121, s[16:17]
	v_cndmask_b32_e64 v204, v98, v118, s[42:43]
	v_cndmask_b32_e64 v205, v99, v119, s[42:43]
	v_cndmask_b32_e64 v206, v100, v120, s[42:43]
	v_cndmask_b32_e64 v207, v101, v121, s[42:43]
	v_pk_mul_f32 v[70:71], v[192:193], v[98:99]
	v_pk_mul_f32 v[72:73], v[194:195], v[100:101]
	v_fmac_f32_dpp v70, v200, v232 row_ror:1 row_mask:0xf bank_mask:0xf
	v_fmac_f32_dpp v71, v201, v233 row_ror:1 row_mask:0xf bank_mask:0xf
	v_fmac_f32_dpp v72, v202, v234 row_ror:1 row_mask:0xf bank_mask:0xf
	v_fmac_f32_dpp v73, v203, v235 row_ror:1 row_mask:0xf bank_mask:0xf
	v_fmac_f32_dpp v70, v204, v224 row_ror:2 row_mask:0xf bank_mask:0xf
	v_fmac_f32_dpp v71, v205, v225 row_ror:2 row_mask:0xf bank_mask:0xf
	v_fmac_f32_dpp v72, v206, v226 row_ror:2 row_mask:0xf bank_mask:0xf
	v_fmac_f32_dpp v73, v207, v227 row_ror:2 row_mask:0xf bank_mask:0xf
	v_pk_mul_f32 v[200:201], v[70:71], s[14:15]
	v_pk_mul_f32 v[202:203], v[72:73], s[14:15]
	v_exp_f32_e32 v200, v200
	v_exp_f32_e32 v201, v201
	v_exp_f32_e32 v202, v202
	v_exp_f32_e32 v203, v203
	v_pk_add_f32 v[200:201], v[200:201], s[24:25]
	v_pk_add_f32 v[202:203], v[202:203], s[24:25]
	v_rcp_f32_e32 v200, v200
	v_rcp_f32_e32 v201, v201
	v_rcp_f32_e32 v202, v202
	v_rcp_f32_e32 v203, v203
	v_pk_mul_f32 v[70:71], v[70:71], v[200:201]
	v_pk_mul_f32 v[72:73], v[72:73], v[202:203]
	v_pk_mul_f32 v[102:103], v[102:103], v[70:71]
	v_pk_mul_f32 v[104:105], v[104:105], v[72:73]
	v_cndmask_b32_e64 v200, v94, v110, s[16:17]
	v_cndmask_b32_e64 v201, v95, v111, s[16:17]
	v_cndmask_b32_e64 v202, v96, v112, s[16:17]
	v_cndmask_b32_e64 v203, v97, v113, s[16:17]
	v_cndmask_b32_e64 v204, v94, v110, s[42:43]
	v_cndmask_b32_e64 v205, v95, v111, s[42:43]
	v_cndmask_b32_e64 v206, v96, v112, s[42:43]
	v_cndmask_b32_e64 v207, v97, v113, s[42:43]
	v_pk_mul_f32 v[70:71], v[196:197], v[94:95]
	v_pk_mul_f32 v[72:73], v[198:199], v[96:97]
	v_fmac_f32_dpp v70, v200, v236 row_ror:1 row_mask:0xf bank_mask:0xf
	v_fmac_f32_dpp v71, v201, v237 row_ror:1 row_mask:0xf bank_mask:0xf
	v_fmac_f32_dpp v72, v202, v238 row_ror:1 row_mask:0xf bank_mask:0xf
	v_fmac_f32_dpp v73, v203, v239 row_ror:1 row_mask:0xf bank_mask:0xf
	v_fmac_f32_dpp v70, v204, v228 row_ror:2 row_mask:0xf bank_mask:0xf
	v_fmac_f32_dpp v71, v205, v229 row_ror:2 row_mask:0xf bank_mask:0xf
	v_fmac_f32_dpp v72, v206, v230 row_ror:2 row_mask:0xf bank_mask:0xf
	v_fmac_f32_dpp v73, v207, v231 row_ror:2 row_mask:0xf bank_mask:0xf
	v_pk_mul_f32 v[200:201], v[70:71], s[14:15]
	v_pk_mul_f32 v[202:203], v[72:73], s[14:15]
	v_exp_f32_e32 v200, v200
	v_exp_f32_e32 v201, v201
	v_exp_f32_e32 v202, v202
	v_exp_f32_e32 v203, v203
	v_pk_add_f32 v[200:201], v[200:201], s[24:25]
	v_pk_add_f32 v[202:203], v[202:203], s[24:25]
	v_rcp_f32_e32 v200, v200
	v_rcp_f32_e32 v201, v201
	v_rcp_f32_e32 v202, v202
	v_rcp_f32_e32 v203, v203
	v_pk_mul_f32 v[70:71], v[70:71], v[200:201]
	v_pk_mul_f32 v[72:73], v[72:73], v[202:203]
	v_pk_mul_f32 v[90:91], v[90:91], v[70:71]
	v_pk_mul_f32 v[92:93], v[92:93], v[72:73]
	v_cvt_pk_bf16_f32 v102, v102, v103
	v_cvt_pk_bf16_f32 v103, v104, v105
	v_cvt_pk_bf16_f32 v104, v90, v91
	v_cvt_pk_bf16_f32 v105, v92, v93
	v_add_co_u32_e32 v170, vcc, 0x56000, v170
	v_addc_co_u32_e32 v171, vcc, 0, v171, vcc
	global_store_dwordx4 v[170:171], v[102:105], off
	v_cvt_pk_bf16_f32 v154, v98, v99
	v_cvt_pk_bf16_f32 v155, v100, v101
	v_cvt_pk_bf16_f32 v156, v94, v95
	v_cvt_pk_bf16_f32 v157, v96, v97
	v_add_co_u32_e32 v188, vcc, 0xfffb4c00, v190
	v_addc_co_u32_e32 v189, vcc, -1, v191, vcc
	s_and_b64 exec, s[22:23], s[42:43]
	global_store_dwordx4 v[188:189], v[154:157], off
	s_mov_b64 exec, s[22:23]
	v_cvt_pk_bf16_f32 v154, v62, v63
	v_cvt_pk_bf16_f32 v155, v64, v65
	v_cvt_pk_bf16_f32 v156, v42, v43
	v_cvt_pk_bf16_f32 v157, v44, v45
	v_cvt_pk_bf16_f32 v204, v82, v83
	v_cvt_pk_bf16_f32 v205, v84, v85
	v_cvt_pk_bf16_f32 v206, v78, v79
	v_cvt_pk_bf16_f32 v207, v80, v81
	v_add_co_u32_e32 v188, vcc, 0x4b400, v190
	v_addc_co_u32_e32 v189, vcc, 0, v191, vcc
	v_add_co_u32_e32 v208, vcc, 0x56000, v190
	v_addc_co_u32_e32 v209, vcc, 0, v191, vcc
	s_andn2_b64 exec, s[22:23], s[40:41]
	global_store_dwordx4 v[188:189], v[154:157], off
	global_store_dwordx4 v[208:209], v[204:207], off
	s_mov_b64 exec, s[22:23]
	s_nop 4
	v_pk_mul_f32 v[70:71], v[192:193], v[62:63]
	v_pk_mul_f32 v[72:73], v[194:195], v[64:65]
	v_fmac_f32_dpp v70, v62, v232 row_ror:1 row_mask:0xf bank_mask:0xf
	v_fmac_f32_dpp v71, v63, v233 row_ror:1 row_mask:0xf bank_mask:0xf
	v_fmac_f32_dpp v72, v64, v234 row_ror:1 row_mask:0xf bank_mask:0xf
	v_fmac_f32_dpp v73, v65, v235 row_ror:1 row_mask:0xf bank_mask:0xf
	v_fmac_f32_dpp v70, v62, v224 row_ror:2 row_mask:0xf bank_mask:0xf
	v_fmac_f32_dpp v71, v63, v225 row_ror:2 row_mask:0xf bank_mask:0xf
	v_fmac_f32_dpp v72, v64, v226 row_ror:2 row_mask:0xf bank_mask:0xf
	v_fmac_f32_dpp v73, v65, v227 row_ror:2 row_mask:0xf bank_mask:0xf
	v_pk_mul_f32 v[200:201], v[70:71], s[14:15]
	v_pk_mul_f32 v[202:203], v[72:73], s[14:15]
	v_exp_f32_e32 v200, v200
	v_exp_f32_e32 v201, v201
	v_exp_f32_e32 v202, v202
	v_exp_f32_e32 v203, v203
	v_pk_add_f32 v[200:201], v[200:201], s[24:25]
	v_pk_add_f32 v[202:203], v[202:203], s[24:25]
	v_rcp_f32_e32 v200, v200
	v_rcp_f32_e32 v201, v201
	v_rcp_f32_e32 v202, v202
	v_rcp_f32_e32 v203, v203
	v_pk_mul_f32 v[70:71], v[70:71], v[200:201]
	v_pk_mul_f32 v[72:73], v[72:73], v[202:203]
	v_pk_mul_f32 v[82:83], v[82:83], v[70:71]
	v_pk_mul_f32 v[84:85], v[84:85], v[72:73]
	v_pk_mul_f32 v[70:71], v[196:197], v[42:43]
; __device__ __forceinline__ unsigned cvt_pk_bf16(float lo, float hi) { unsigned r; asm volatile("v_cvt_pk_bf16_f32 %0, %1, %2" : "=v"(r) : "v"(lo), "v"(hi)); return r; }
; __device__ __forceinline__ float sigmoidf_(float x) { return __builtin_amdgcn_rcpf(1.0f + __expf(-x)); }
; __device__ __forceinline__ float dpp_ror1(float x) { return __int_as_float(__builtin_amdgcn_update_dpp(0, __float_as_int(x), 0x121, 0xF, 0xF, true)); }
;     __device__ __forceinline__ void operator()(const f32x4 (&acc)[2][2][4][2], const Unit& u, int wr, int wc, int fr, int fq) const {
;     ...
;             for (int m = 0; m < 4; ++m) {
;                 const size_t row = (size_t)(u.pm * BM + ai * HALF + wr * 64 + m * 16 + fr);
;                 float hg[8];
; #pragma unroll
;                 for (int n = 0; n < 2; ++n)
; #pragma unroll
;                     for (int i = 0; i < 4; ++i) {
;                         const float cur = acc[ai][0][m][n][i], prv = (m > 0) ? acc[ai][0][m > 0 ? m - 1 : 0][n][i] : cur;
;                         const float r1c = dpp_ror1(cur), r1p = dpp_ror1(prv), r2c = dpp_ror2(cur), r2p = dpp_ror2(prv);
;                         const float tm1 = f1 ? r1c : r1p, tm2 = f2 ? r2c : r2p;
;                         const float cv = w0[n][i] * tm2 + w1[n][i] * tm1 + w2[n][i] * cur;
;                         hg[4 * n + i] = cv * sigmoidf_(cv) * acc[ai][1][m][n][i];
;                     }
;                 if (m == 0 && fr < 2) {
;                     const f32x4 a0 = acc[ai][0][0][0], a1 = acc[ai][0][0][1], v0 = acc[ai][1][0][0], v1 = acc[ai][1][0][1];
;                     u32x4 wa, wv; wa.x = cvt_pk_bf16(a0[0], a0[1]); wa.y = cvt_pk_bf16(a0[2], a0[3]); wa.z = cvt_pk_bf16(a1[0], a1[1]); wa.w = cvt_pk_bf16(a1[2], a1[3]);
;                     wv.x = cvt_pk_bf16(v0[0], v0[1]); wv.y = cvt_pk_bf16(v0[2], v0[3]); wv.z = cvt_pk_bf16(v1[0], v1[1]); wv.w = cvt_pk_bf16(v1[2], v1[3]);
;                     *(u32x4*)(side + ((size_t)blk * 6 + 2 + fr) * ldh + ch0) = wa; *(u32x4*)(side + ((size_t)blk * 6 + 4 + fr) * ldh + ch0) = wv;
;                 } else {
;                     u32x4 w; w.x = cvt_pk_bf16(hg[0], hg[1]); w.y = cvt_pk_bf16(hg[2], hg[3]); w.z = cvt_pk_bf16(hg[4], hg[5]); w.w = cvt_pk_bf16(hg[6], hg[7]);
;                     *(u32x4*)(HG + row * ldh + ch0) = w;
;                 }
	v_pk_mul_f32 v[72:73], v[198:199], v[44:45]
	v_fmac_f32_dpp v70, v42, v236 row_ror:1 row_mask:0xf bank_mask:0xf
	v_fmac_f32_dpp v71, v43, v237 row_ror:1 row_mask:0xf bank_mask:0xf
	v_fmac_f32_dpp v72, v44, v238 row_ror:1 row_mask:0xf bank_mask:0xf
	v_fmac_f32_dpp v73, v45, v239 row_ror:1 row_mask:0xf bank_mask:0xf
	v_fmac_f32_dpp v70, v42, v228 row_ror:2 row_mask:0xf bank_mask:0xf
	v_fmac_f32_dpp v71, v43, v229 row_ror:2 row_mask:0xf bank_mask:0xf
	v_fmac_f32_dpp v72, v44, v230 row_ror:2 row_mask:0xf bank_mask:0xf
	v_fmac_f32_dpp v73, v45, v231 row_ror:2 row_mask:0xf bank_mask:0xf
	v_pk_mul_f32 v[200:201], v[70:71], s[14:15]
	v_pk_mul_f32 v[202:203], v[72:73], s[14:15]
	v_exp_f32_e32 v200, v200
	v_exp_f32_e32 v201, v201
	v_exp_f32_e32 v202, v202
	v_exp_f32_e32 v203, v203
	v_pk_add_f32 v[200:201], v[200:201], s[24:25]
	v_pk_add_f32 v[202:203], v[202:203], s[24:25]
	v_rcp_f32_e32 v200, v200
	v_rcp_f32_e32 v201, v201
	v_rcp_f32_e32 v202, v202
	v_rcp_f32_e32 v203, v203
	v_pk_mul_f32 v[70:71], v[70:71], v[200:201]
	v_pk_mul_f32 v[72:73], v[72:73], v[202:203]
	v_pk_mul_f32 v[78:79], v[78:79], v[70:71]
	v_pk_mul_f32 v[80:81], v[80:81], v[72:73]
	v_cvt_pk_bf16_f32 v82, v82, v83
	v_cvt_pk_bf16_f32 v83, v84, v85
	v_cvt_pk_bf16_f32 v84, v78, v79
	v_cvt_pk_bf16_f32 v85, v80, v81
	v_add_co_u32_e32 v170, vcc, 0x1ae000, v170
	v_addc_co_u32_e32 v171, vcc, 0, v171, vcc
	s_and_b64 exec, s[22:23], s[40:41]
	global_store_dwordx4 v[170:171], v[82:85], off
	s_mov_b64 exec, s[22:23]
	v_cndmask_b32_e64 v200, v58, v62, s[16:17]
	v_cndmask_b32_e64 v201, v59, v63, s[16:17]
	v_cndmask_b32_e64 v202, v60, v64, s[16:17]
	v_cndmask_b32_e64 v203, v61, v65, s[16:17]
	v_cndmask_b32_e64 v204, v58, v62, s[42:43]
	v_cndmask_b32_e64 v205, v59, v63, s[42:43]
	v_cndmask_b32_e64 v206, v60, v64, s[42:43]
	v_cndmask_b32_e64 v207, v61, v65, s[42:43]
	v_pk_mul_f32 v[70:71], v[192:193], v[58:59]
	v_pk_mul_f32 v[72:73], v[194:195], v[60:61]
	v_fmac_f32_dpp v70, v200, v232 row_ror:1 row_mask:0xf bank_mask:0xf
	v_fmac_f32_dpp v71, v201, v233 row_ror:1 row_mask:0xf bank_mask:0xf
	v_fmac_f32_dpp v72, v202, v234 row_ror:1 row_mask:0xf bank_mask:0xf
	v_fmac_f32_dpp v73, v203, v235 row_ror:1 row_mask:0xf bank_mask:0xf
	v_fmac_f32_dpp v70, v204, v224 row_ror:2 row_mask:0xf bank_mask:0xf
	v_fmac_f32_dpp v71, v205, v225 row_ror:2 row_mask:0xf bank_mask:0xf
	v_fmac_f32_dpp v72, v206, v226 row_ror:2 row_mask:0xf bank_mask:0xf
	v_fmac_f32_dpp v73, v207, v227 row_ror:2 row_mask:0xf bank_mask:0xf
	v_pk_mul_f32 v[200:201], v[70:71], s[14:15]
	v_pk_mul_f32 v[202:203], v[72:73], s[14:15]
	v_exp_f32_e32 v200, v200
	v_exp_f32_e32 v201, v201
	v_exp_f32_e32 v202, v202
	v_exp_f32_e32 v203, v203
	v_pk_add_f32 v[200:201], v[200:201], s[24:25]
	v_pk_add_f32 v[202:203], v[202:203], s[24:25]
	v_rcp_f32_e32 v200, v200
	v_rcp_f32_e32 v201, v201
	v_rcp_f32_e32 v202, v202
	v_rcp_f32_e32 v203, v203
	v_pk_mul_f32 v[70:71], v[70:71], v[200:201]
	v_pk_mul_f32 v[72:73], v[72:73], v[202:203]
	v_pk_mul_f32 v[46:47], v[46:47], v[70:71]
	v_pk_mul_f32 v[48:49], v[48:49], v[72:73]
	v_cndmask_b32_e64 v200, v38, v42, s[16:17]
	v_cndmask_b32_e64 v201, v39, v43, s[16:17]
	v_cndmask_b32_e64 v202, v40, v44, s[16:17]
	v_cndmask_b32_e64 v203, v41, v45, s[16:17]
	v_cndmask_b32_e64 v204, v38, v42, s[42:43]
	v_cndmask_b32_e64 v205, v39, v43, s[42:43]
	v_cndmask_b32_e64 v206, v40, v44, s[42:43]
	v_cndmask_b32_e64 v207, v41, v45, s[42:43]
	v_pk_mul_f32 v[70:71], v[196:197], v[38:39]
	v_pk_mul_f32 v[72:73], v[198:199], v[40:41]
	v_fmac_f32_dpp v70, v200, v236 row_ror:1 row_mask:0xf bank_mask:0xf
	v_fmac_f32_dpp v71, v201, v237 row_ror:1 row_mask:0xf bank_mask:0xf
	v_fmac_f32_dpp v72, v202, v238 row_ror:1 row_mask:0xf bank_mask:0xf
	v_fmac_f32_dpp v73, v203, v239 row_ror:1 row_mask:0xf bank_mask:0xf
	v_fmac_f32_dpp v70, v204, v228 row_ror:2 row_mask:0xf bank_mask:0xf
	v_fmac_f32_dpp v71, v205, v229 row_ror:2 row_mask:0xf bank_mask:0xf
	v_fmac_f32_dpp v72, v206, v230 row_ror:2 row_mask:0xf bank_mask:0xf
	v_fmac_f32_dpp v73, v207, v231 row_ror:2 row_mask:0xf bank_mask:0xf
	v_pk_mul_f32 v[200:201], v[70:71], s[14:15]
	v_pk_mul_f32 v[202:203], v[72:73], s[14:15]
	v_exp_f32_e32 v200, v200
	v_exp_f32_e32 v201, v201
	v_exp_f32_e32 v202, v202
	v_exp_f32_e32 v203, v203
	v_pk_add_f32 v[200:201], v[200:201], s[24:25]
	v_pk_add_f32 v[202:203], v[202:203], s[24:25]
	v_rcp_f32_e32 v200, v200
	v_rcp_f32_e32 v201, v201
	v_rcp_f32_e32 v202, v202
	v_rcp_f32_e32 v203, v203
	v_pk_mul_f32 v[70:71], v[70:71], v[200:201]
	v_pk_mul_f32 v[72:73], v[72:73], v[202:203]
	v_pk_mul_f32 v[34:35], v[34:35], v[70:71]
	v_pk_mul_f32 v[36:37], v[36:37], v[72:73]
	v_cvt_pk_bf16_f32 v46, v46, v47
	v_cvt_pk_bf16_f32 v47, v48, v49
	v_cvt_pk_bf16_f32 v48, v34, v35
	v_cvt_pk_bf16_f32 v49, v36, v37
	v_add_co_u32_e32 v170, vcc, 0x56000, v170
	v_addc_co_u32_e32 v171, vcc, 0, v171, vcc
	global_store_dwordx4 v[170:171], v[46:49], off
	v_cndmask_b32_e64 v200, v30, v58, s[16:17]
	v_cndmask_b32_e64 v201, v31, v59, s[16:17]
	v_cndmask_b32_e64 v202, v32, v60, s[16:17]
	v_cndmask_b32_e64 v203, v33, v61, s[16:17]
	v_cndmask_b32_e64 v204, v30, v58, s[42:43]
	v_cndmask_b32_e64 v205, v31, v59, s[42:43]
	v_cndmask_b32_e64 v206, v32, v60, s[42:43]
	v_cndmask_b32_e64 v207, v33, v61, s[42:43]
	v_pk_mul_f32 v[70:71], v[192:193], v[30:31]
	v_pk_mul_f32 v[72:73], v[194:195], v[32:33]
	v_fmac_f32_dpp v70, v200, v232 row_ror:1 row_mask:0xf bank_mask:0xf
	v_fmac_f32_dpp v71, v201, v233 row_ror:1 row_mask:0xf bank_mask:0xf
	v_fmac_f32_dpp v72, v202, v234 row_ror:1 row_mask:0xf bank_mask:0xf
	v_fmac_f32_dpp v73, v203, v235 row_ror:1 row_mask:0xf bank_mask:0xf
	v_fmac_f32_dpp v70, v204, v224 row_ror:2 row_mask:0xf bank_mask:0xf
; __device__ __forceinline__ float sigmoidf_(float x) { return __builtin_amdgcn_rcpf(1.0f + __expf(-x)); }
;     __device__ __forceinline__ void operator()(const f32x4 (&acc)[2][2][4][2], const Unit& u, int wr, int wc, int fr, int fq) const {
;     ...
;             for (int m = 0; m < 4; ++m) {
;                 const size_t row = (size_t)(u.pm * BM + ai * HALF + wr * 64 + m * 16 + fr);
;                 float hg[8];
; #pragma unroll
;                 for (int n = 0; n < 2; ++n)
; #pragma unroll
;                     for (int i = 0; i < 4; ++i) {
;                         const float cur = acc[ai][0][m][n][i], prv = (m > 0) ? acc[ai][0][m > 0 ? m - 1 : 0][n][i] : cur;
;                         const float r1c = dpp_ror1(cur), r1p = dpp_ror1(prv), r2c = dpp_ror2(cur), r2p = dpp_ror2(prv);
;                         const float tm1 = f1 ? r1c : r1p, tm2 = f2 ? r2c : r2p;
;                         const float cv = w0[n][i] * tm2 + w1[n][i] * tm1 + w2[n][i] * cur;
;                         hg[4 * n + i] = cv * sigmoidf_(cv) * acc[ai][1][m][n][i];
;                     }
;                 if (m == 0 && fr < 2) {
;                     const f32x4 a0 = acc[ai][0][0][0], a1 = acc[ai][0][0][1], v0 = acc[ai][1][0][0], v1 = acc[ai][1][0][1];
;                     u32x4 wa, wv; wa.x = cvt_pk_bf16(a0[0], a0[1]); wa.y = cvt_pk_bf16(a0[2], a0[3]); wa.z = cvt_pk_bf16(a1[0], a1[1]); wa.w = cvt_pk_bf16(a1[2], a1[3]);
;                     wv.x = cvt_pk_bf16(v0[0], v0[1]); wv.y = cvt_pk_bf16(v0[2], v0[3]); wv.z = cvt_pk_bf16(v1[0], v1[1]); wv.w = cvt_pk_bf16(v1[2], v1[3]);
;                     *(u32x4*)(side + ((size_t)blk * 6 + 2 + fr) * ldh + ch0) = wa; *(u32x4*)(side + ((size_t)blk * 6 + 4 + fr) * ldh + ch0) = wv;
;                 } else {
;                     u32x4 w; w.x = cvt_pk_bf16(hg[0], hg[1]); w.y = cvt_pk_bf16(hg[2], hg[3]); w.z = cvt_pk_bf16(hg[4], hg[5]); w.w = cvt_pk_bf16(hg[6], hg[7]);
;                     *(u32x4*)(HG + row * ldh + ch0) = w;
;                 }
;                 if (m == 3 && fr >= 14) {
;                     const f32x4 a0 = acc[ai][0][3][0], a1 = acc[ai][0][3][1];
;                     u32x4 wa; wa.x = cvt_pk_bf16(a0[0], a0[1]); wa.y = cvt_pk_bf16(a0[2], a0[3]); wa.z = cvt_pk_bf16(a1[0], a1[1]); wa.w = cvt_pk_bf16(a1[2], a1[3]);
;                     *(u32x4*)(side + ((size_t)blk * 6 + (fr - 14)) * ldh + ch0) = wa;
;                 }
	v_fmac_f32_dpp v71, v205, v225 row_ror:2 row_mask:0xf bank_mask:0xf
	v_fmac_f32_dpp v72, v206, v226 row_ror:2 row_mask:0xf bank_mask:0xf
	v_fmac_f32_dpp v73, v207, v227 row_ror:2 row_mask:0xf bank_mask:0xf
	v_pk_mul_f32 v[200:201], v[70:71], s[14:15]
	v_pk_mul_f32 v[202:203], v[72:73], s[14:15]
	v_exp_f32_e32 v200, v200
	v_exp_f32_e32 v201, v201
	v_exp_f32_e32 v202, v202
	v_exp_f32_e32 v203, v203
	v_pk_add_f32 v[200:201], v[200:201], s[24:25]
	v_pk_add_f32 v[202:203], v[202:203], s[24:25]
	v_rcp_f32_e32 v200, v200
	v_rcp_f32_e32 v201, v201
	v_rcp_f32_e32 v202, v202
	v_rcp_f32_e32 v203, v203
	v_pk_mul_f32 v[70:71], v[70:71], v[200:201]
	v_pk_mul_f32 v[72:73], v[72:73], v[202:203]
	v_pk_mul_f32 v[26:27], v[26:27], v[70:71]
	v_pk_mul_f32 v[28:29], v[28:29], v[72:73]
	v_cndmask_b32_e64 v200, v22, v38, s[16:17]
	v_cndmask_b32_e64 v201, v23, v39, s[16:17]
	v_cndmask_b32_e64 v202, v24, v40, s[16:17]
	v_cndmask_b32_e64 v203, v25, v41, s[16:17]
	v_cndmask_b32_e64 v204, v22, v38, s[42:43]
	v_cndmask_b32_e64 v205, v23, v39, s[42:43]
	v_cndmask_b32_e64 v206, v24, v40, s[42:43]
	v_cndmask_b32_e64 v207, v25, v41, s[42:43]
	v_pk_mul_f32 v[70:71], v[196:197], v[22:23]
	v_pk_mul_f32 v[72:73], v[198:199], v[24:25]
	v_fmac_f32_dpp v70, v200, v236 row_ror:1 row_mask:0xf bank_mask:0xf
	v_fmac_f32_dpp v71, v201, v237 row_ror:1 row_mask:0xf bank_mask:0xf
	v_fmac_f32_dpp v72, v202, v238 row_ror:1 row_mask:0xf bank_mask:0xf
	v_fmac_f32_dpp v73, v203, v239 row_ror:1 row_mask:0xf bank_mask:0xf
	v_fmac_f32_dpp v70, v204, v228 row_ror:2 row_mask:0xf bank_mask:0xf
	v_fmac_f32_dpp v71, v205, v229 row_ror:2 row_mask:0xf bank_mask:0xf
	v_fmac_f32_dpp v72, v206, v230 row_ror:2 row_mask:0xf bank_mask:0xf
	v_fmac_f32_dpp v73, v207, v231 row_ror:2 row_mask:0xf bank_mask:0xf
	v_pk_mul_f32 v[200:201], v[70:71], s[14:15]
	v_pk_mul_f32 v[202:203], v[72:73], s[14:15]
	v_exp_f32_e32 v200, v200
	v_exp_f32_e32 v201, v201
	v_exp_f32_e32 v202, v202
	v_exp_f32_e32 v203, v203
	v_pk_add_f32 v[200:201], v[200:201], s[24:25]
	v_pk_add_f32 v[202:203], v[202:203], s[24:25]
	v_rcp_f32_e32 v200, v200
	v_rcp_f32_e32 v201, v201
	v_rcp_f32_e32 v202, v202
	v_rcp_f32_e32 v203, v203
	v_pk_mul_f32 v[70:71], v[70:71], v[200:201]
	v_pk_mul_f32 v[72:73], v[72:73], v[202:203]
	v_pk_mul_f32 v[18:19], v[18:19], v[70:71]
	v_pk_mul_f32 v[20:21], v[20:21], v[72:73]
	v_cvt_pk_bf16_f32 v26, v26, v27
	v_cvt_pk_bf16_f32 v27, v28, v29
	v_cvt_pk_bf16_f32 v28, v18, v19
	v_cvt_pk_bf16_f32 v29, v20, v21
	v_add_co_u32_e32 v170, vcc, 0x56000, v170
	v_addc_co_u32_e32 v171, vcc, 0, v171, vcc
	global_store_dwordx4 v[170:171], v[26:29], off
	v_cndmask_b32_e64 v200, v10, v30, s[16:17]
	v_cndmask_b32_e64 v201, v11, v31, s[16:17]
	v_cndmask_b32_e64 v202, v12, v32, s[16:17]
	v_cndmask_b32_e64 v203, v13, v33, s[16:17]
	v_cndmask_b32_e64 v204, v10, v30, s[42:43]
	v_cndmask_b32_e64 v205, v11, v31, s[42:43]
	v_cndmask_b32_e64 v206, v12, v32, s[42:43]
	v_cndmask_b32_e64 v207, v13, v33, s[42:43]
	v_pk_mul_f32 v[70:71], v[192:193], v[10:11]
	v_pk_mul_f32 v[72:73], v[194:195], v[12:13]
	v_fmac_f32_dpp v70, v200, v232 row_ror:1 row_mask:0xf bank_mask:0xf
	v_fmac_f32_dpp v71, v201, v233 row_ror:1 row_mask:0xf bank_mask:0xf
	v_fmac_f32_dpp v72, v202, v234 row_ror:1 row_mask:0xf bank_mask:0xf
	v_fmac_f32_dpp v73, v203, v235 row_ror:1 row_mask:0xf bank_mask:0xf
	v_fmac_f32_dpp v70, v204, v224 row_ror:2 row_mask:0xf bank_mask:0xf
	v_fmac_f32_dpp v71, v205, v225 row_ror:2 row_mask:0xf bank_mask:0xf
	v_fmac_f32_dpp v72, v206, v226 row_ror:2 row_mask:0xf bank_mask:0xf
	v_fmac_f32_dpp v73, v207, v227 row_ror:2 row_mask:0xf bank_mask:0xf
	v_pk_mul_f32 v[200:201], v[70:71], s[14:15]
	v_pk_mul_f32 v[202:203], v[72:73], s[14:15]
	v_exp_f32_e32 v200, v200
	v_exp_f32_e32 v201, v201
	v_exp_f32_e32 v202, v202
	v_exp_f32_e32 v203, v203
	v_pk_add_f32 v[200:201], v[200:201], s[24:25]
	v_pk_add_f32 v[202:203], v[202:203], s[24:25]
	v_rcp_f32_e32 v200, v200
	v_rcp_f32_e32 v201, v201
	v_rcp_f32_e32 v202, v202
	v_rcp_f32_e32 v203, v203
	v_pk_mul_f32 v[70:71], v[70:71], v[200:201]
	v_pk_mul_f32 v[72:73], v[72:73], v[202:203]
	v_pk_mul_f32 v[14:15], v[14:15], v[70:71]
	v_pk_mul_f32 v[16:17], v[16:17], v[72:73]
	v_cndmask_b32_e64 v200, v6, v22, s[16:17]
	v_cndmask_b32_e64 v201, v7, v23, s[16:17]
	v_cndmask_b32_e64 v202, v8, v24, s[16:17]
	v_cndmask_b32_e64 v203, v9, v25, s[16:17]
	v_cndmask_b32_e64 v204, v6, v22, s[42:43]
	v_cndmask_b32_e64 v205, v7, v23, s[42:43]
	v_cndmask_b32_e64 v206, v8, v24, s[42:43]
	v_cndmask_b32_e64 v207, v9, v25, s[42:43]
	v_pk_mul_f32 v[70:71], v[196:197], v[6:7]
	v_pk_mul_f32 v[72:73], v[198:199], v[8:9]
	v_fmac_f32_dpp v70, v200, v236 row_ror:1 row_mask:0xf bank_mask:0xf
	v_fmac_f32_dpp v71, v201, v237 row_ror:1 row_mask:0xf bank_mask:0xf
	v_fmac_f32_dpp v72, v202, v238 row_ror:1 row_mask:0xf bank_mask:0xf
	v_fmac_f32_dpp v73, v203, v239 row_ror:1 row_mask:0xf bank_mask:0xf
	v_fmac_f32_dpp v70, v204, v228 row_ror:2 row_mask:0xf bank_mask:0xf
	v_fmac_f32_dpp v71, v205, v229 row_ror:2 row_mask:0xf bank_mask:0xf
	v_fmac_f32_dpp v72, v206, v230 row_ror:2 row_mask:0xf bank_mask:0xf
	v_fmac_f32_dpp v73, v207, v231 row_ror:2 row_mask:0xf bank_mask:0xf
	v_pk_mul_f32 v[200:201], v[70:71], s[14:15]
	v_pk_mul_f32 v[202:203], v[72:73], s[14:15]
	v_exp_f32_e32 v200, v200
	v_exp_f32_e32 v201, v201
	v_exp_f32_e32 v202, v202
	v_exp_f32_e32 v203, v203
	v_pk_add_f32 v[200:201], v[200:201], s[24:25]
	v_pk_add_f32 v[202:203], v[202:203], s[24:25]
	v_rcp_f32_e32 v200, v200
	v_rcp_f32_e32 v201, v201
	v_rcp_f32_e32 v202, v202
	v_rcp_f32_e32 v203, v203
	v_pk_mul_f32 v[70:71], v[70:71], v[200:201]
	v_pk_mul_f32 v[72:73], v[72:73], v[202:203]
	v_pk_mul_f32 v[2:3], v[2:3], v[70:71]
	v_pk_mul_f32 v[4:5], v[4:5], v[72:73]
	v_cvt_pk_bf16_f32 v14, v14, v15
	v_cvt_pk_bf16_f32 v15, v16, v17
	v_cvt_pk_bf16_f32 v16, v2, v3
	v_cvt_pk_bf16_f32 v17, v4, v5
	v_add_co_u32_e32 v170, vcc, 0x56000, v170
	v_addc_co_u32_e32 v171, vcc, 0, v171, vcc
	global_store_dwordx4 v[170:171], v[14:17], off
	v_cvt_pk_bf16_f32 v154, v10, v11
	v_cvt_pk_bf16_f32 v155, v12, v13
	v_cvt_pk_bf16_f32 v156, v6, v7
	v_cvt_pk_bf16_f32 v157, v8, v9
	v_add_co_u32_e32 v188, vcc, 0xffff5400, v190
	v_addc_co_u32_e32 v189, vcc, -1, v191, vcc
	s_and_b64 exec, s[22:23], s[42:43]
	global_store_dwordx4 v[188:189], v[154:157], off
	s_mov_b64 exec, s[22:23]
	s_andn2_b64 vcc, exec, s[20:21]
	s_mov_b64 s[20:21], -1
	s_cbranch_vccnz .LBB0_699
	s_andn2_b64 vcc, exec, s[46:47]
	s_cbranch_vccnz .LBB0_698
	s_barrier
	s_branch .LBB0_698
